# EpiOutFin phase A: xin loads of the next row group issued before the current one is consumed (two groups in flight)
# speedup vs baseline: 1.0098x; 1.0098x over previous
; #define PG8_LAS __attribute__((address_space(3)))
;     __device__ __forceinline__ void fused(f32x4 (&acc)[2][2][4][2], const Unit& u, int wr, int wc, int fr, int fq, PG8_LAS unsigned char* lds, int wid, int lane) const {
;         const int row0 = u.pm * BM + wr * 64 + fr; const int col0 = u.pn * BM + wc * 32 + 4 * fq;
;         const int b = (u.pm * BM) >> 11;
;         PG8_LAS float* P = (PG8_LAS float*)lds; PG8_LAS float* S = P + 1024;
;         f32x4 gt[2][2];
; #pragma unroll
;         for (int bj = 0; bj < 2; ++bj)
; #pragma unroll
;             for (int n = 0; n < 2; ++n) gt[bj][n] = *(const f32x4*)(modf + (size_t)b * 3072 + 2048 + col0 + bj * HALF + 16 * n);
; #pragma unroll
;         for (int ai = 0; ai < 2; ++ai)
; #pragma unroll
;             for (int m = 0; m < 4; ++m) { const size_t ro = (size_t)(row0 + ai * HALF + m * 16) * 1024 + col0; float s = 0.f;
; #pragma unroll
;                 for (int bj = 0; bj < 2; ++bj)
; #pragma unroll
;                     for (int n = 0; n < 2; ++n) { const f32x4 xi = __builtin_nontemporal_load((const f32x4*)(xin + ro + bj * HALF + 16 * n));
;                         const f32x4 v = xi + gt[bj][n] * acc[ai][bj][m][n]; acc[ai][bj][m][n] = v;
;                         s += (v[0] * v[0] + v[1] * v[1]) + (v[2] * v[2] + v[3] * v[3]); }
;                 s += __shfl_xor(s, 16); s += __shfl_xor(s, 32);
;                 if (fq == 0) P[(ai * HALF + wr * 64 + m * 16 + fr) * 4 + wc] = s; }
.LBB0_669:
	v_readlane_b32 s30, v255, 27
	v_readlane_b32 s31, v255, 28
	s_mul_i32 s2, s30, 0x18000
	v_readlane_b32 s30, v253, 48
	v_readlane_b32 s31, v253, 49
	s_add_u32 s2, s30, s2
	s_addc_u32 s4, s31, 0
	s_lshl_b32 s30, s20, 8
	s_lshl_b32 s21, s27, 5
	s_add_i32 s33, s30, s5
	s_lshl_b32 s30, s26, 8
	s_or_b32 s21, s30, s21
	v_lshrrev_b32_e32 v76, 2, v191
	v_and_or_b32 v160, v76, 12, s21
	s_ashr_i32 s21, s20, 3
	s_mul_hi_i32 s31, s21, 0x3000
	s_mulk_i32 s21, 0x3000
	s_add_u32 s30, s2, s21
	v_ashrrev_i32_e32 v161, 31, v160
	s_addc_u32 s31, s4, s31
	v_lshlrev_b64 v[148:149], 2, v[160:161]
	v_lshl_add_u64 v[76:77], s[30:31], 0, v[148:149]
	s_mov_b64 s[30:31], 0x2000
	s_movk_i32 s2, 0x2000
	v_lshl_add_u64 v[78:79], v[76:77], 0, s[30:31]
	v_add_co_u32_e32 v76, vcc, s2, v76
	v_and_b32_e32 v151, 64, v224
	s_nop 0
	v_addc_co_u32_e32 v77, vcc, 0, v77, vcc
	v_xor_b32_e32 v150, 16, v224
	v_add_u32_e32 v151, 64, v151
	v_cmp_lt_i32_e32 vcc, v150, v151
	v_or_b32_e32 v164, s33, v168
	v_ashrrev_i32_e32 v165, 31, v164
	v_cndmask_b32_e32 v150, v224, v150, vcc
	v_lshlrev_b32_e32 v170, 2, v150
	v_xor_b32_e32 v150, 32, v224
	v_cmp_lt_i32_e32 vcc, v150, v151
	s_waitcnt vmcnt(0)
	s_barrier
	global_load_dwordx4 v[100:103], v[76:77], off
	global_load_dwordx4 v[92:95], v[78:79], off offset:64
	global_load_dwordx4 v[84:87], v[78:79], off offset:512
	s_nop 0
	global_load_dwordx4 v[76:79], v[78:79], off offset:576
	v_cndmask_b32_e32 v150, v224, v150, vcc
	v_lshlrev_b32_e32 v171, 2, v150
	v_lshlrev_b64 v[150:151], 12, v[164:165]
	v_lshl_add_u64 v[154:155], s[18:19], 0, v[150:151]
	v_lshl_add_u64 v[158:159], v[154:155], 0, v[148:149]
	v_mov_b32_e32 v182, v158
	v_mov_b32_e32 v183, v159
	global_load_dwordx4 v[212:215], v[158:159], off nt
	global_load_dwordx4 v[216:219], v[158:159], off offset:64 nt
	global_load_dwordx4 v[220:223], v[158:159], off offset:512 nt
	global_load_dwordx4 v[242:245], v[158:159], off offset:576 nt
	s_mov_b64 s[98:99], 0x10000
	v_lshl_add_u64 v[180:181], v[182:183], 0, s[98:99]
	global_load_dwordx4 v[194:197], v[180:181], off nt
	global_load_dwordx4 v[198:201], v[180:181], off offset:64 nt
	global_load_dwordx4 v[202:205], v[180:181], off offset:512 nt
	global_load_dwordx4 v[206:209], v[180:181], off offset:576 nt
	s_lshl_b32 s2, s27, 2
	v_and_b32_e32 v169, 63, v191
	s_add_i32 s2, s2, 0
	v_cmp_gt_u32_e32 vcc, 16, v169
	v_lshl_add_u32 v172, v152, 4, s2
	s_waitcnt vmcnt(7)
	v_pk_fma_f32 v[146:147], v[146:147], v[102:103], v[214:215]
	v_pk_fma_f32 v[144:145], v[144:145], v[100:101], v[212:213]
	v_mul_f32_e32 v154, v147, v147
	v_mul_f32_e32 v153, v145, v145
	v_fmac_f32_e32 v153, v144, v144
	v_fmac_f32_e32 v154, v146, v146
	v_add_f32_e32 v153, v153, v154
	s_waitcnt vmcnt(6)
	v_pk_fma_f32 v[142:143], v[142:143], v[94:95], v[218:219]
	v_pk_fma_f32 v[140:141], v[140:141], v[92:93], v[216:217]
	v_mul_f32_e32 v155, v143, v143
	v_mul_f32_e32 v154, v141, v141
	v_fmac_f32_e32 v154, v140, v140
	v_fmac_f32_e32 v155, v142, v142
	v_add_f32_e32 v154, v154, v155
	v_add_f32_e32 v153, v153, v154
	s_waitcnt vmcnt(5)
	v_pk_fma_f32 v[138:139], v[138:139], v[86:87], v[222:223]
	v_pk_fma_f32 v[136:137], v[136:137], v[84:85], v[220:221]
	v_mul_f32_e32 v155, v139, v139
	v_mul_f32_e32 v154, v137, v137
	v_fmac_f32_e32 v154, v136, v136
	v_fmac_f32_e32 v155, v138, v138
	v_add_f32_e32 v154, v154, v155
	v_add_f32_e32 v153, v153, v154
	s_waitcnt vmcnt(4)
	v_pk_fma_f32 v[134:135], v[134:135], v[78:79], v[244:245]
	v_pk_fma_f32 v[132:133], v[132:133], v[76:77], v[242:243]
	v_mul_f32_e32 v155, v135, v135
	v_mul_f32_e32 v154, v133, v133
	v_fmac_f32_e32 v154, v132, v132
	v_fmac_f32_e32 v155, v134, v134
	v_add_f32_e32 v154, v154, v155
	v_add_f32_e32 v153, v153, v154
	ds_bpermute_b32 v154, v170, v153
	s_waitcnt lgkmcnt(0)
	v_add_f32_e32 v153, v153, v154
	ds_bpermute_b32 v154, v171, v153
	s_and_saveexec_b64 s[30:31], vcc
	s_cbranch_execz .LBB0_671
	s_waitcnt lgkmcnt(0)
	v_add_f32_e32 v152, v153, v154
	ds_write_b32 v172, v152
.LBB0_671:
	s_or_b64 exec, exec, s[30:31]
	v_or_b32_e32 v152, 16, v164
	v_ashrrev_i32_e32 v153, 31, v152
	v_lshlrev_b64 v[152:153], 12, v[152:153]
	s_waitcnt lgkmcnt(0)
	v_lshl_add_u64 v[154:155], s[18:19], 0, v[152:153]
	v_lshl_add_u64 v[158:159], v[160:161], 2, v[154:155]
	s_mov_b64 s[98:99], 0x20000
	v_lshl_add_u64 v[180:181], v[182:183], 0, s[98:99]
	global_load_dwordx4 v[212:215], v[180:181], off nt
	global_load_dwordx4 v[216:219], v[180:181], off offset:64 nt
	global_load_dwordx4 v[220:223], v[180:181], off offset:512 nt
	global_load_dwordx4 v[242:245], v[180:181], off offset:576 nt
	s_waitcnt vmcnt(7)
	v_pk_fma_f32 v[130:131], v[130:131], v[102:103], v[196:197]
	v_pk_fma_f32 v[128:129], v[128:129], v[100:101], v[194:195]
	v_mul_f32_e32 v155, v131, v131
	v_mul_f32_e32 v154, v129, v129
	v_fmac_f32_e32 v154, v128, v128
	v_fmac_f32_e32 v155, v130, v130
	v_add_f32_e32 v162, v154, v155
	s_waitcnt vmcnt(6)
	v_pk_fma_f32 v[126:127], v[126:127], v[94:95], v[200:201]
	v_pk_fma_f32 v[124:125], v[124:125], v[92:93], v[198:199]
	v_mul_f32_e32 v155, v127, v127
	v_mul_f32_e32 v154, v125, v125
	v_fmac_f32_e32 v154, v124, v124
	v_fmac_f32_e32 v155, v126, v126
	v_add_f32_e32 v154, v154, v155
	v_add_f32_e32 v162, v162, v154
	s_waitcnt vmcnt(5)
	v_pk_fma_f32 v[122:123], v[122:123], v[86:87], v[204:205]
	v_pk_fma_f32 v[120:121], v[120:121], v[84:85], v[202:203]
	v_mul_f32_e32 v155, v123, v123
	v_mul_f32_e32 v154, v121, v121
	v_fmac_f32_e32 v154, v120, v120
	v_fmac_f32_e32 v155, v122, v122
	v_add_f32_e32 v154, v154, v155
	v_add_f32_e32 v162, v162, v154
	s_waitcnt vmcnt(4)
	v_pk_fma_f32 v[118:119], v[118:119], v[78:79], v[208:209]
	v_pk_fma_f32 v[154:155], v[116:117], v[76:77], v[206:207]
	v_mul_f32_e32 v117, v119, v119
	v_mul_f32_e32 v116, v155, v155
	v_fmac_f32_e32 v116, v154, v154
	v_fmac_f32_e32 v117, v118, v118
	v_add_f32_e32 v116, v116, v117
	v_add_f32_e32 v116, v162, v116
	ds_bpermute_b32 v117, v170, v116
	s_waitcnt lgkmcnt(0)
	v_add_f32_e32 v116, v116, v117
	ds_bpermute_b32 v117, v171, v116
	s_and_saveexec_b64 s[30:31], vcc
	s_cbranch_execz .LBB0_673
	s_waitcnt lgkmcnt(0)
	v_add_f32_e32 v116, v116, v117
	ds_write_b32 v172, v116 offset:256
;     __device__ __forceinline__ void fused(f32x4 (&acc)[2][2][4][2], const Unit& u, int wr, int wc, int fr, int fq, PG8_LAS unsigned char* lds, int wid, int lane) const {
;     ...
;         for (int ai = 0; ai < 2; ++ai)
; #pragma unroll
;             for (int m = 0; m < 4; ++m) { const size_t ro = (size_t)(row0 + ai * HALF + m * 16) * 1024 + col0; float s = 0.f;
; #pragma unroll
;                 for (int bj = 0; bj < 2; ++bj)
; #pragma unroll
;                     for (int n = 0; n < 2; ++n) { const f32x4 xi = __builtin_nontemporal_load((const f32x4*)(xin + ro + bj * HALF + 16 * n));
;                         const f32x4 v = xi + gt[bj][n] * acc[ai][bj][m][n]; acc[ai][bj][m][n] = v;
;                         s += (v[0] * v[0] + v[1] * v[1]) + (v[2] * v[2] + v[3] * v[3]); }
;                 s += __shfl_xor(s, 16); s += __shfl_xor(s, 32);
;                 if (fq == 0) P[(ai * HALF + wr * 64 + m * 16 + fr) * 4 + wc] = s; }
.LBB0_673:
	s_or_b64 exec, exec, s[30:31]
	v_or_b32_e32 v116, 32, v164
	s_waitcnt lgkmcnt(0)
	v_ashrrev_i32_e32 v117, 31, v116
	v_lshlrev_b64 v[116:117], 12, v[116:117]
	v_lshl_add_u64 v[156:157], s[18:19], 0, v[116:117]
	v_lshl_add_u64 v[162:163], v[160:161], 2, v[156:157]
	s_mov_b64 s[98:99], 0x30000
	v_lshl_add_u64 v[180:181], v[182:183], 0, s[98:99]
	global_load_dwordx4 v[194:197], v[180:181], off nt
	global_load_dwordx4 v[198:201], v[180:181], off offset:64 nt
	global_load_dwordx4 v[202:205], v[180:181], off offset:512 nt
	global_load_dwordx4 v[206:209], v[180:181], off offset:576 nt
	s_waitcnt vmcnt(7)
	v_pk_fma_f32 v[114:115], v[114:115], v[102:103], v[214:215]
	s_waitcnt vmcnt(6)
	v_pk_fma_f32 v[110:111], v[110:111], v[94:95], v[218:219]
	v_pk_fma_f32 v[108:109], v[108:109], v[92:93], v[216:217]
	v_pk_fma_f32 v[156:157], v[112:113], v[100:101], v[212:213]
	v_mul_f32_e32 v113, v115, v115
	v_mul_f32_e32 v112, v157, v157
	v_fmac_f32_e32 v112, v156, v156
	v_fmac_f32_e32 v113, v114, v114
	v_add_f32_e32 v112, v112, v113
	v_mul_f32_e32 v113, v109, v109
	v_mul_f32_e32 v158, v111, v111
	v_fmac_f32_e32 v113, v108, v108
	v_fmac_f32_e32 v158, v110, v110
	v_add_f32_e32 v113, v113, v158
	v_add_f32_e32 v112, v112, v113
	s_waitcnt vmcnt(5)
	v_pk_fma_f32 v[106:107], v[106:107], v[86:87], v[222:223]
	v_pk_fma_f32 v[104:105], v[104:105], v[84:85], v[220:221]
	v_mul_f32_e32 v113, v105, v105
	v_mul_f32_e32 v158, v107, v107
	v_fmac_f32_e32 v113, v104, v104
	v_fmac_f32_e32 v158, v106, v106
	v_add_f32_e32 v113, v113, v158
	v_add_f32_e32 v158, v112, v113
	s_waitcnt vmcnt(4)
	v_pk_fma_f32 v[98:99], v[98:99], v[78:79], v[244:245]
	v_pk_fma_f32 v[112:113], v[96:97], v[76:77], v[242:243]
	v_mul_f32_e32 v97, v99, v99
	v_mul_f32_e32 v96, v113, v113
	v_fmac_f32_e32 v96, v112, v112
	v_fmac_f32_e32 v97, v98, v98
	v_add_f32_e32 v96, v96, v97
	v_add_f32_e32 v96, v158, v96
	ds_bpermute_b32 v97, v170, v96
	s_waitcnt lgkmcnt(0)
	v_add_f32_e32 v96, v96, v97
	ds_bpermute_b32 v97, v171, v96
	s_and_saveexec_b64 s[30:31], vcc
	s_cbranch_execz .LBB0_675
	s_waitcnt lgkmcnt(0)
	v_add_f32_e32 v96, v96, v97
	ds_write_b32 v172, v96 offset:512
.LBB0_675:
	s_or_b64 exec, exec, s[30:31]
	v_or_b32_e32 v96, 48, v164
	s_waitcnt lgkmcnt(0)
	v_ashrrev_i32_e32 v97, 31, v96
	v_lshlrev_b64 v[96:97], 12, v[96:97]
	v_lshl_add_u64 v[158:159], s[18:19], 0, v[96:97]
	v_lshl_add_u64 v[158:159], v[160:161], 2, v[158:159]
	s_mov_b64 s[98:99], 0x80000
	v_lshl_add_u64 v[180:181], v[182:183], 0, s[98:99]
	global_load_dwordx4 v[212:215], v[180:181], off nt
	global_load_dwordx4 v[216:219], v[180:181], off offset:64 nt
	global_load_dwordx4 v[220:223], v[180:181], off offset:512 nt
	global_load_dwordx4 v[242:245], v[180:181], off offset:576 nt
	s_waitcnt vmcnt(7)
	v_pk_fma_f32 v[90:91], v[90:91], v[102:103], v[196:197]
	v_pk_fma_f32 v[88:89], v[88:89], v[100:101], v[194:195]
	v_mul_f32_e32 v162, v89, v89
	v_mul_f32_e32 v163, v91, v91
	v_fmac_f32_e32 v162, v88, v88
	v_fmac_f32_e32 v163, v90, v90
	v_add_f32_e32 v162, v162, v163
	s_waitcnt vmcnt(6)
	v_pk_fma_f32 v[82:83], v[82:83], v[94:95], v[200:201]
	v_pk_fma_f32 v[80:81], v[80:81], v[92:93], v[198:199]
	v_mul_f32_e32 v163, v81, v81
	v_mul_f32_e32 v166, v83, v83
	v_fmac_f32_e32 v163, v80, v80
	v_fmac_f32_e32 v166, v82, v82
	v_add_f32_e32 v163, v163, v166
	v_add_f32_e32 v162, v162, v163
	s_waitcnt vmcnt(5)
	v_pk_fma_f32 v[74:75], v[74:75], v[86:87], v[204:205]
	v_pk_fma_f32 v[72:73], v[72:73], v[84:85], v[202:203]
	v_mul_f32_e32 v163, v73, v73
	v_mul_f32_e32 v166, v75, v75
	v_fmac_f32_e32 v163, v72, v72
	v_fmac_f32_e32 v166, v74, v74
	v_add_f32_e32 v163, v163, v166
	v_add_f32_e32 v162, v162, v163
	s_waitcnt vmcnt(4)
	v_pk_fma_f32 v[70:71], v[70:71], v[78:79], v[208:209]
	v_pk_fma_f32 v[68:69], v[68:69], v[76:77], v[206:207]
	v_mul_f32_e32 v159, v71, v71
	v_mul_f32_e32 v158, v69, v69
	v_fmac_f32_e32 v158, v68, v68
	v_fmac_f32_e32 v159, v70, v70
	v_add_f32_e32 v158, v158, v159
	v_add_f32_e32 v158, v162, v158
	ds_bpermute_b32 v159, v170, v158
	s_waitcnt lgkmcnt(0)
	v_add_f32_e32 v158, v158, v159
	ds_bpermute_b32 v159, v171, v158
	s_and_saveexec_b64 s[30:31], vcc
	s_cbranch_execz .LBB0_677
	s_waitcnt lgkmcnt(0)
	v_add_f32_e32 v158, v158, v159
	ds_write_b32 v172, v158 offset:768
.LBB0_677:
	s_or_b64 exec, exec, s[30:31]
	v_lshlrev_b64 v[162:163], 12, v[164:165]
	s_mov_b64 s[30:31], 0x80000
	s_waitcnt lgkmcnt(0)
	v_lshl_add_u64 v[158:159], v[162:163], 0, s[30:31]
	v_lshl_add_u64 v[166:167], s[18:19], 0, v[158:159]
	v_lshl_add_u64 v[166:167], v[160:161], 2, v[166:167]
	s_mov_b64 s[98:99], 0x90000
	v_lshl_add_u64 v[180:181], v[182:183], 0, s[98:99]
	global_load_dwordx4 v[194:197], v[180:181], off nt
	global_load_dwordx4 v[198:201], v[180:181], off offset:64 nt
	global_load_dwordx4 v[202:205], v[180:181], off offset:512 nt
	global_load_dwordx4 v[206:209], v[180:181], off offset:576 nt
	s_waitcnt vmcnt(7)
	v_pk_fma_f32 v[66:67], v[66:67], v[102:103], v[214:215]
	v_pk_fma_f32 v[64:65], v[64:65], v[100:101], v[212:213]
	v_mul_f32_e32 v174, v67, v67
	v_mul_f32_e32 v173, v65, v65
	v_fmac_f32_e32 v173, v64, v64
	v_fmac_f32_e32 v174, v66, v66
	v_add_f32_e32 v173, v173, v174
	s_waitcnt vmcnt(6)
	v_pk_fma_f32 v[62:63], v[62:63], v[94:95], v[218:219]
	v_pk_fma_f32 v[60:61], v[60:61], v[92:93], v[216:217]
	v_mul_f32_e32 v175, v63, v63
	v_mul_f32_e32 v174, v61, v61
	v_fmac_f32_e32 v174, v60, v60
	v_fmac_f32_e32 v175, v62, v62
	v_add_f32_e32 v174, v174, v175
	v_add_f32_e32 v173, v173, v174
	s_waitcnt vmcnt(5)
	v_pk_fma_f32 v[58:59], v[58:59], v[86:87], v[222:223]
	v_pk_fma_f32 v[56:57], v[56:57], v[84:85], v[220:221]
	v_mul_f32_e32 v175, v59, v59
	v_mul_f32_e32 v174, v57, v57
	v_fmac_f32_e32 v174, v56, v56
	v_fmac_f32_e32 v175, v58, v58
	v_add_f32_e32 v174, v174, v175
	v_add_f32_e32 v173, v173, v174
	s_waitcnt vmcnt(4)
	v_pk_fma_f32 v[54:55], v[54:55], v[78:79], v[244:245]
	v_pk_fma_f32 v[52:53], v[52:53], v[76:77], v[242:243]
	v_mul_f32_e32 v167, v55, v55
	v_mul_f32_e32 v166, v53, v53
	v_fmac_f32_e32 v166, v52, v52
	v_fmac_f32_e32 v167, v54, v54
	v_add_f32_e32 v166, v166, v167
	v_add_f32_e32 v166, v173, v166
	ds_bpermute_b32 v167, v170, v166
	s_waitcnt lgkmcnt(0)
	v_add_f32_e32 v166, v166, v167
	ds_bpermute_b32 v167, v171, v166
	s_and_saveexec_b64 s[30:31], vcc
	s_cbranch_execz .LBB0_679
	s_waitcnt lgkmcnt(0)
	v_add_f32_e32 v166, v166, v167
	ds_write_b32 v172, v166 offset:2048
;     __device__ __forceinline__ void fused(f32x4 (&acc)[2][2][4][2], const Unit& u, int wr, int wc, int fr, int fq, PG8_LAS unsigned char* lds, int wid, int lane) const {
;     ...
;         for (int ai = 0; ai < 2; ++ai)
; #pragma unroll
;             for (int m = 0; m < 4; ++m) { const size_t ro = (size_t)(row0 + ai * HALF + m * 16) * 1024 + col0; float s = 0.f;
; #pragma unroll
;                 for (int bj = 0; bj < 2; ++bj)
; #pragma unroll
;                     for (int n = 0; n < 2; ++n) { const f32x4 xi = __builtin_nontemporal_load((const f32x4*)(xin + ro + bj * HALF + 16 * n));
;                         const f32x4 v = xi + gt[bj][n] * acc[ai][bj][m][n]; acc[ai][bj][m][n] = v;
;                         s += (v[0] * v[0] + v[1] * v[1]) + (v[2] * v[2] + v[3] * v[3]); }
;                 s += __shfl_xor(s, 16); s += __shfl_xor(s, 32);
;                 if (fq == 0) P[(ai * HALF + wr * 64 + m * 16 + fr) * 4 + wc] = s; }
.LBB0_679:
	s_or_b64 exec, exec, s[30:31]
	s_mov_b64 s[30:31], 0x90000
	v_lshl_add_u64 v[162:163], v[162:163], 0, s[30:31]
	s_waitcnt lgkmcnt(0)
	v_lshl_add_u64 v[166:167], s[18:19], 0, v[162:163]
	v_lshl_add_u64 v[166:167], v[160:161], 2, v[166:167]
	s_mov_b64 s[98:99], 0xa0000
	v_lshl_add_u64 v[180:181], v[182:183], 0, s[98:99]
	global_load_dwordx4 v[212:215], v[180:181], off nt
	global_load_dwordx4 v[216:219], v[180:181], off offset:64 nt
	global_load_dwordx4 v[220:223], v[180:181], off offset:512 nt
	global_load_dwordx4 v[242:245], v[180:181], off offset:576 nt
	s_waitcnt vmcnt(7)
	v_pk_fma_f32 v[50:51], v[50:51], v[102:103], v[196:197]
	v_pk_fma_f32 v[48:49], v[48:49], v[100:101], v[194:195]
	v_mul_f32_e32 v174, v51, v51
	v_mul_f32_e32 v173, v49, v49
	v_fmac_f32_e32 v173, v48, v48
	v_fmac_f32_e32 v174, v50, v50
	v_add_f32_e32 v173, v173, v174
	s_waitcnt vmcnt(6)
	v_pk_fma_f32 v[46:47], v[46:47], v[94:95], v[200:201]
	v_pk_fma_f32 v[44:45], v[44:45], v[92:93], v[198:199]
	v_mul_f32_e32 v175, v47, v47
	v_mul_f32_e32 v174, v45, v45
	v_fmac_f32_e32 v174, v44, v44
	v_fmac_f32_e32 v175, v46, v46
	v_add_f32_e32 v174, v174, v175
	v_add_f32_e32 v173, v173, v174
	s_waitcnt vmcnt(5)
	v_pk_fma_f32 v[42:43], v[42:43], v[86:87], v[204:205]
	v_pk_fma_f32 v[40:41], v[40:41], v[84:85], v[202:203]
	v_mul_f32_e32 v175, v43, v43
	v_mul_f32_e32 v174, v41, v41
	v_fmac_f32_e32 v174, v40, v40
	v_fmac_f32_e32 v175, v42, v42
	v_add_f32_e32 v174, v174, v175
	v_add_f32_e32 v173, v173, v174
	s_waitcnt vmcnt(4)
	v_pk_fma_f32 v[38:39], v[38:39], v[78:79], v[208:209]
	v_pk_fma_f32 v[36:37], v[36:37], v[76:77], v[206:207]
	v_mul_f32_e32 v167, v39, v39
	v_mul_f32_e32 v166, v37, v37
	v_fmac_f32_e32 v166, v36, v36
	v_fmac_f32_e32 v167, v38, v38
	v_add_f32_e32 v166, v166, v167
	v_add_f32_e32 v166, v173, v166
	ds_bpermute_b32 v167, v170, v166
	s_waitcnt lgkmcnt(0)
	v_add_f32_e32 v166, v166, v167
	ds_bpermute_b32 v167, v171, v166
	s_and_saveexec_b64 s[30:31], vcc
	s_cbranch_execz .LBB0_681
	s_waitcnt lgkmcnt(0)
	v_add_f32_e32 v166, v166, v167
	ds_write_b32 v172, v166 offset:2304
.LBB0_681:
	s_or_b64 exec, exec, s[30:31]
	s_waitcnt lgkmcnt(0)
	v_lshlrev_b64 v[166:167], 12, v[164:165]
	s_mov_b64 s[30:31], 0xa0000
	v_lshl_add_u64 v[164:165], v[166:167], 0, s[30:31]
	v_lshl_add_u64 v[174:175], s[18:19], 0, v[164:165]
	v_lshl_add_u64 v[178:179], v[160:161], 2, v[174:175]
	s_mov_b64 s[98:99], 0xb0000
	v_lshl_add_u64 v[180:181], v[182:183], 0, s[98:99]
	global_load_dwordx4 v[194:197], v[180:181], off nt
	global_load_dwordx4 v[198:201], v[180:181], off offset:64 nt
	global_load_dwordx4 v[202:205], v[180:181], off offset:512 nt
	global_load_dwordx4 v[206:209], v[180:181], off offset:576 nt
	s_waitcnt vmcnt(7)
	v_pk_fma_f32 v[34:35], v[34:35], v[102:103], v[214:215]
	v_pk_fma_f32 v[32:33], v[32:33], v[100:101], v[212:213]
	v_mul_f32_e32 v174, v35, v35
	v_mul_f32_e32 v173, v33, v33
	v_fmac_f32_e32 v173, v32, v32
	v_fmac_f32_e32 v174, v34, v34
	v_add_f32_e32 v173, v173, v174
	s_waitcnt vmcnt(6)
	v_pk_fma_f32 v[30:31], v[30:31], v[94:95], v[218:219]
	v_pk_fma_f32 v[28:29], v[28:29], v[92:93], v[216:217]
	v_mul_f32_e32 v175, v31, v31
	v_mul_f32_e32 v174, v29, v29
	v_fmac_f32_e32 v174, v28, v28
	v_fmac_f32_e32 v175, v30, v30
	v_add_f32_e32 v174, v174, v175
	v_add_f32_e32 v173, v173, v174
	s_waitcnt vmcnt(5)
	v_pk_fma_f32 v[26:27], v[26:27], v[86:87], v[222:223]
	v_pk_fma_f32 v[24:25], v[24:25], v[84:85], v[220:221]
	v_mul_f32_e32 v175, v27, v27
	v_mul_f32_e32 v174, v25, v25
	v_fmac_f32_e32 v174, v24, v24
	v_fmac_f32_e32 v175, v26, v26
	v_add_f32_e32 v174, v174, v175
	v_add_f32_e32 v173, v173, v174
	s_waitcnt vmcnt(4)
	v_pk_fma_f32 v[22:23], v[22:23], v[78:79], v[244:245]
	v_pk_fma_f32 v[20:21], v[20:21], v[76:77], v[242:243]
	v_mul_f32_e32 v175, v23, v23
	v_mul_f32_e32 v174, v21, v21
	v_fmac_f32_e32 v174, v20, v20
	v_fmac_f32_e32 v175, v22, v22
	v_add_f32_e32 v174, v174, v175
	v_add_f32_e32 v173, v173, v174
	ds_bpermute_b32 v174, v170, v173
	s_waitcnt lgkmcnt(0)
	v_add_f32_e32 v173, v173, v174
	ds_bpermute_b32 v174, v171, v173
	s_and_saveexec_b64 s[30:31], vcc
	s_cbranch_execz .LBB0_683
	s_waitcnt lgkmcnt(0)
	v_add_f32_e32 v173, v173, v174
	ds_write_b32 v172, v173 offset:2560
.LBB0_683:
	s_or_b64 exec, exec, s[30:31]
	s_mov_b64 s[30:31], 0xb0000
	v_lshl_add_u64 v[166:167], v[166:167], 0, s[30:31]
	s_waitcnt lgkmcnt(0)
	v_lshl_add_u64 v[174:175], s[18:19], 0, v[166:167]
	v_lshl_add_u64 v[160:161], v[160:161], 2, v[174:175]
	s_waitcnt vmcnt(3)
	v_pk_fma_f32 v[102:103], v[18:19], v[102:103], v[196:197]
	v_pk_fma_f32 v[100:101], v[16:17], v[100:101], v[194:195]
	v_mul_f32_e32 v17, v103, v103
	v_mul_f32_e32 v16, v101, v101
	v_fmac_f32_e32 v16, v100, v100
	v_fmac_f32_e32 v17, v102, v102
	v_add_f32_e32 v173, v16, v17
	s_waitcnt vmcnt(2)
	v_pk_fma_f32 v[94:95], v[14:15], v[94:95], v[200:201]
	v_pk_fma_f32 v[92:93], v[12:13], v[92:93], v[198:199]
	v_mul_f32_e32 v13, v95, v95
	v_mul_f32_e32 v12, v93, v93
	v_fmac_f32_e32 v12, v92, v92
	v_fmac_f32_e32 v13, v94, v94
	v_add_f32_e32 v12, v12, v13
	v_add_f32_e32 v16, v173, v12
	s_waitcnt vmcnt(1)
	v_pk_fma_f32 v[86:87], v[10:11], v[86:87], v[204:205]
	v_pk_fma_f32 v[84:85], v[8:9], v[84:85], v[202:203]
	v_mul_f32_e32 v9, v87, v87
	v_mul_f32_e32 v8, v85, v85
	v_fmac_f32_e32 v8, v84, v84
	v_fmac_f32_e32 v9, v86, v86
	v_add_f32_e32 v8, v8, v9
	v_add_f32_e32 v12, v16, v8
	s_waitcnt vmcnt(0)
	v_pk_fma_f32 v[78:79], v[6:7], v[78:79], v[208:209]
	v_pk_fma_f32 v[76:77], v[4:5], v[76:77], v[206:207]
	v_mul_f32_e32 v5, v79, v79
	v_mul_f32_e32 v4, v77, v77
	v_fmac_f32_e32 v4, v76, v76
	v_fmac_f32_e32 v5, v78, v78
	v_add_f32_e32 v4, v4, v5
	v_add_f32_e32 v4, v12, v4
	ds_bpermute_b32 v5, v170, v4
	s_waitcnt lgkmcnt(0)
	v_add_f32_e32 v4, v4, v5
	ds_bpermute_b32 v5, v171, v4
	s_and_saveexec_b64 s[18:19], vcc
	s_cbranch_execz .LBB0_685
	s_waitcnt lgkmcnt(0)
	v_add_f32_e32 v4, v4, v5
	ds_write_b32 v172, v4 offset:2816
